# v65 + P5 ninth-round units handed out by an atomic ticket to the first workgroups that finish seven units (dynamic tail) instead of bx<64
# baseline (speedup 1.0000x reference)
.LBB0_1077:
	s_add_i32 s46, s46, 1
	s_mul_i32 s4, s46, s49
	s_mul_hi_u32 s5, s46, s50
	s_add_i32 s5, s5, s4
	s_mul_i32 s4, s46, s50
	s_add_u32 s28, s4, s83
	s_addc_u32 s29, s5, 0
	s_cmp_eq_u32 s46, 8
	s_cbranch_scc0 .Ldyn5_h
	s_add_u32 s28, s98, 0x800
	s_mov_b32 s29, 0
.Ldyn5_h:
	v_cmp_gt_i64_e32 vcc, s[28:29], v[142:143]
	v_cmp_lt_i64_e64 s[4:5], s[28:29], v[140:141]
	s_cbranch_vccnz .LBB0_1079
	s_ashr_i32 s24, s28, 31
	s_lshr_b32 s24, s24, 29
	s_add_i32 s24, s28, s24
	s_ashr_i32 s25, s24, 3
	s_and_b32 s24, s24, -8
	s_sub_i32 s24, s28, s24
	s_cmp_lt_i32 s24, 0
	s_cselect_b32 s26, s51, 0x108
	s_mul_i32 s24, s24, s26
	s_add_i32 s24, s24, s25
	s_ashr_i32 s25, s24, 31
	s_lshr_b32 s25, s25, 25
	s_add_i32 s25, s24, s25
	s_ashr_i32 s26, s25, 7
	s_lshl_b32 s26, s26, 3
	s_sub_i32 s27, 0x84, s26
	s_min_i32 s27, s27, 8
	s_abs_i32 s28, s27
	v_cvt_f32_u32_e32 v0, s28
	s_sub_i32 s30, 0, s28
	s_and_b32 s25, s25, 0xffffff80
	s_sub_i32 s25, s24, s25
	v_rcp_iflag_f32_e32 v0, v0
	s_abs_i32 s24, s25
	s_xor_b32 s29, s25, s27
	s_ashr_i32 s29, s29, 31
	v_mul_f32_e32 v0, 0x4f7ffffe, v0
	v_cvt_u32_f32_e32 v0, v0
	s_nop 0
	v_readfirstlane_b32 s31, v0
	s_mul_i32 s30, s30, s31
	s_mul_hi_u32 s30, s31, s30
	s_add_i32 s31, s31, s30
	s_mul_hi_u32 s30, s24, s31
	s_mul_i32 s31, s30, s28
	s_sub_i32 s24, s24, s31
	s_add_i32 s38, s30, 1
	s_sub_i32 s31, s24, s28
	s_cmp_ge_u32 s24, s28
	s_cselect_b32 s30, s38, s30
	s_cselect_b32 s24, s31, s24
	s_add_i32 s31, s30, 1
	s_cmp_ge_u32 s24, s28
	s_cselect_b32 s24, s31, s30
	s_xor_b32 s24, s24, s29
	s_sub_i32 s24, s24, s29
	s_mul_i32 s27, s24, s27
	s_sub_i32 s25, s25, s27
	s_add_i32 s26, s26, s25

.LBB0_1083:
	s_cmp_lg_u32 s46, 7
	s_cbranch_scc1 .Ldyn5_skip
	s_add_u32 s100, s74, 0x80300
	s_addc_u32 s101, s75, 0
	v_cmp_eq_u32_e64 s[98:99], 0, v179
	s_and_saveexec_b64 s[98:99], s[98:99]
	s_cbranch_execz .Ldyn5_a
	v_mov_b32_e32 v150, 0
	v_mov_b32_e32 v151, 1
	global_atomic_add v151, v150, v151, s[100:101] sc0
	v_mov_b32_e32 v152, 0x23f00
	s_waitcnt vmcnt(0)
	ds_write_b32 v152, v151
	s_waitcnt lgkmcnt(0)
.Ldyn5_a:
	s_mov_b64 exec, s[98:99]
	s_barrier
	v_mov_b32_e32 v152, 0x23f00
	ds_read_b32 v151, v152
	s_waitcnt lgkmcnt(0)
	v_readfirstlane_b32 s98, v151
